# v3 + workgroups relabelled rank*8+xcc at start; phase8 block map batch-per-XCC; barriers after P5,P7,phase8,P9 made XCC-local (no L2 writeback, no cross-XCC round)
# speedup vs baseline: 1.0032x; 1.0032x over previous
; #define PG8_LAS __attribute__((address_space(3)))
; __device__ __forceinline__ int tid_v() { int t = threadIdx.x; asm volatile("" : "+v"(t)); return t; }
; __device__ __forceinline__ int bid_s() { int b = blockIdx.x; asm volatile("" : "+s"(b)); return b; }
; __device__ __forceinline__ unsigned xb_add(unsigned* p, unsigned v) { return __hip_atomic_fetch_add(p, v, __ATOMIC_RELAXED, __HIP_MEMORY_SCOPE_AGENT); }
; __device__ __forceinline__ unsigned xb_xcc_id() { return (unsigned)__builtin_amdgcn_s_getreg((3 << 11) | 20) & 0xFu; }
; #define WSP() ((unsigned char*)karg_ptr<35 * 8>())
; __device__ __forceinline__ XcdBarrier xcd_barrier_post(unsigned* bar, volatile LAS unsigned* st) {
;     XcdBarrier b; b.bar = bar; b.x = xb_xcc_id(); b.st = st;
;     if (threadIdx.x == 0) (void)xb_add(&bar[XB_XCNT(b.x)], 1u);
;     return b;
; }
; __global__ void __launch_bounds__(512, 2) mega(Params p) {
;     ...
;     constexpr int G = 256; const int c = (int)bid_s();
;     volatile PG8_LAS unsigned* bst = (volatile PG8_LAS unsigned*)(lds + 131072);
;     if (tid_v() < 4) bst[tid_v()] = 0u;
;     __syncthreads();
;     const XcdBarrier xb = xcd_barrier_post((unsigned*)(WSP() + BAR_OFF), bst);
.LBB0_2:
	s_or_b64 exec, exec, s[2:3]
	s_waitcnt lgkmcnt(0)
	s_barrier
	s_load_dwordx2 s[14:15], s[0:1], 0x118
	s_waitcnt lgkmcnt(0)
	s_add_u32 s16, s14, 0x7e30000
	s_getreg_b32 s2, hwreg(HW_REG_XCC_ID, 0, 4)
	s_addc_u32 s17, s15, 0
	s_and_b32 s28, s2, 15
	s_mov_b32 s5, 0
	v_cmp_eq_u32_e64 s[8:9], 0, v179
	s_mov_b64 s[2:3], exec
	s_nop 0
	v_writelane_b32 v254, s8, 0
	s_nop 1
	v_writelane_b32 v254, s9, 1
	s_and_b64 s[8:9], s[2:3], s[8:9]
	s_mov_b64 exec, s[8:9]
	s_cbranch_execz .LBB0_5
	s_mov_b64 s[8:9], exec
	v_mbcnt_lo_u32_b32 v1, s8, 0
	v_mbcnt_hi_u32_b32 v1, s9, v1
	v_cmp_eq_u32_e32 vcc, 0, v1
	s_and_b64 s[10:11], exec, vcc
	s_mov_b64 exec, s[10:11]
	s_cbranch_execz .LBB0_5
	s_lshl_b32 s4, s28, 8
	s_bcnt1_i32_b64 s8, s[8:9]
	v_mov_b32_e32 v1, s4
	v_mov_b32_e32 v2, s8
	global_atomic_add v3, v1, v2, s[16:17] offset:1024 sc0
	s_waitcnt vmcnt(0)
	v_lshlrev_b32_e32 v3, 3, v3
	v_or_b32_e32 v3, s28, v3
	v_mov_b32_e32 v1, 0x2000c
	ds_write_b32 v1, v3
	s_waitcnt lgkmcnt(0)
.LBB0_5:
	s_or_b64 exec, exec, s[2:3]
	s_barrier
	v_mov_b32_e32 v1, 0x2000c
	ds_read_b32 v1, v1
	s_waitcnt lgkmcnt(0)
	v_readfirstlane_b32 s87, v1
	s_mov_b32 s88, s87
	s_abs_i32 s29, s72
	v_cvt_f32_u32_e32 v1, s29
	s_sub_i32 s2, 0, s29
	s_lshl_b32 s74, s72, 6
	s_mov_b64 s[8:9], -1
	v_rcp_iflag_f32_e32 v1, v1
	s_mov_b32 s30, 0x8c00
	v_mov_b32_e32 v11, 0
	s_movk_i32 s31, 0x104
	v_mul_f32_e32 v1, 0x4f7ffffe, v1
	v_cvt_u32_f32_e32 v1, v1
	s_mov_b32 s33, 0x20000
	s_movk_i32 s34, 0x5800
	s_movk_i32 s35, 0x1600
	v_readfirstlane_b32 s3, v1
	s_mul_i32 s2, s2, s3
	s_mul_hi_u32 s2, s3, s2
	s_add_i32 s36, s3, s2
	s_movk_i32 s37, 0x4000
	s_mov_b32 s38, 0x10000
	s_mov_b32 s2, s5
	s_mov_b32 s39, 0
	s_branch .LBB0_7

; __device__ __forceinline__ unsigned xb_ld(unsigned* p)              { return __hip_atomic_load(p, __ATOMIC_RELAXED, __HIP_MEMORY_SCOPE_AGENT); }
; __device__ __forceinline__ unsigned xb_add(unsigned* p, unsigned v) { return __hip_atomic_fetch_add(p, v, __ATOMIC_RELAXED, __HIP_MEMORY_SCOPE_AGENT); }
; #define XB_SPIN(cond, bar) do { unsigned _sp = 0; while (cond) { __builtin_amdgcn_s_sleep(1); \
;     if ((++_sp & 255u) == 0u) { if (xb_ld(&(bar)[XB_TMO])) break; if (_sp > XB_SPIN_CAP) { atomicAdd(&(bar)[XB_TMO], 1u); break; } } } } while (0)
; __device__ __forceinline__ void xcd_barrier(const XcdBarrier& b) {
;     ...
;         const unsigned old = xb_add(&bar[XB_XSUB(b.x)], 1u);
;         const unsigned gen = old / nloc;
;         if (old + 1u == (gen + 1u) * nloc) {
;             __builtin_amdgcn_fence(__ATOMIC_RELEASE, "agent");
;             asm volatile("s_waitcnt vmcnt(0)" ::: "memory");
;             const unsigned og = xb_add(&bar[XB_TOP], 1u);
;             const unsigned tg = og / nx;
;             if (og + 1u == (tg + 1u) * nx) xb_add(&bar[XB_TOPGEN], 1u);
;             else XB_SPIN(xb_ld(&bar[XB_TOPGEN]) == tg, bar);
;             __builtin_amdgcn_fence(__ATOMIC_ACQUIRE, "agent");
;             xb_add(&bar[XB_XGEN(b.x)], 1u);
;             asm volatile("s_waitcnt vmcnt(0)" ::: "memory");
;         } else {
;             XB_SPIN(xb_ld(&bar[XB_XGEN(b.x)]) == gen, bar);
;             __builtin_amdgcn_fence(__ATOMIC_ACQUIRE, "agent");
;             asm volatile("s_waitcnt vmcnt(0)" ::: "memory");
;         }
.LBB0_1057:
	s_andn2_saveexec_b64 s[2:3], s[2:3]
	s_cbranch_execz .LBB0_1077
	s_mov_b64 s[2:3], exec
	s_branch .LBB0_1074

; __device__ __forceinline__ int tid_v() { int t = threadIdx.x; asm volatile("" : "+v"(t)); return t; }
; __device__ __forceinline__ int bid_s() { int b = blockIdx.x; asm volatile("" : "+s"(b)); return b; }
; #define WSP() ((unsigned char*)karg_ptr<35 * 8>())
; __device__ __forceinline__ void phase8(int l, int s) {
;     const Bufs B = make_bufs(WSP(), l);
;     const float* cw = IN(27) + (size_t)l * 3 * 5632; const float* cb = IN(28) + (size_t)l * 5632;
;     const int tid = tid_v();
;     if (tid >= 352) return;
;     const int j0 = tid * 8;
;     f32x4 wg[3][2], wv[3][2], bg[2], bv[2];
; #pragma unroll
;     for (int e = 0; e < 2; ++e) {
;         bg[e] = *(const f32x4*)(cb + j0 + 4 * e); bv[e] = *(const f32x4*)(cb + 2816 + j0 + 4 * e);
; #pragma unroll
;         for (int tap = 0; tap < 3; ++tap) { wg[tap][e] = *(const f32x4*)(cw + (size_t)tap * 5632 + j0 + 4 * e); wv[tap][e] = *(const f32x4*)(cw + (size_t)tap * 5632 + 2816 + j0 + 4 * e); }
;     }
;     const u32x4 zero4 = {0u, 0u, 0u, 0u};
;     for (int blk = bid_s(); blk < MS / 64; blk += gridDim.x) {
;         const int mbeg = blk * 64, b = mbeg >> 11, tl0 = mbeg & 2047;
.LBB0_1239:
	s_or_b64 exec, exec, s[16:17]
	s_waitcnt lgkmcnt(0)
	s_barrier
	s_load_dwordx2 s[16:17], s[0:1], 0x118
	s_waitcnt lgkmcnt(0)
	s_load_dwordx2 s[20:21], s[0:1], 0xd8
	s_waitcnt lgkmcnt(0)
	s_load_dwordx2 s[2:3], s[0:1], 0xe0
	s_waitcnt lgkmcnt(0)
	v_mov_b32_e32 v0, v179
	s_movk_i32 s18, 0x160
	s_nop 0
	v_cmp_gt_i32_e32 vcc, s18, v0
	s_and_saveexec_b64 s[18:19], vcc
	s_cbranch_execz .LBB0_1254
	s_mul_i32 s23, s69, 0x10800
	s_mul_hi_u32 s22, s69, 0x10800
	s_add_u32 s20, s20, s23
	s_addc_u32 s21, s21, s22
	s_mul_i32 s23, s69, 0x5800
	v_lshlrev_b32_e32 v64, 3, v0
	s_mul_hi_u32 s22, s69, 0x5800
	s_add_u32 s2, s2, s23
	v_ashrrev_i32_e32 v65, 31, v64
	s_addc_u32 s3, s3, s22
	v_lshlrev_b64 v[0:1], 2, v[64:65]
	v_lshl_add_u64 v[8:9], s[2:3], 0, v[0:1]
	s_mov_b64 s[22:23], 0x2c00
	s_movk_i32 s2, 0x2000
	v_lshl_add_u64 v[12:13], v[8:9], 0, s[22:23]
	v_lshl_add_u64 v[56:57], s[20:21], 0, v[0:1]
	global_load_dwordx4 v[0:3], v[8:9], off offset:16
	global_load_dwordx4 v[4:7], v[8:9], off
	v_add_co_u32_e32 v8, vcc, s2, v8
	v_lshl_add_u64 v[28:29], v[56:57], 0, s[22:23]
	s_nop 0
	v_addc_co_u32_e32 v9, vcc, 0, v9, vcc
	v_add_co_u32_e32 v24, vcc, s2, v56
	s_mov_b64 s[2:3], 0x5800
	s_nop 0
	v_addc_co_u32_e32 v25, vcc, 0, v57, vcc
	v_lshl_add_u64 v[36:37], v[56:57], 0, s[2:3]
	s_movk_i32 s2, 0x5000
	v_add_co_u32_e32 v32, vcc, s2, v56
	s_mov_b64 s[2:3], 0x8400
	s_nop 0
	v_addc_co_u32_e32 v33, vcc, 0, v57, vcc
	v_lshl_add_u64 v[44:45], v[56:57], 0, s[2:3]
	s_mov_b32 s2, 0x8000
	v_add_co_u32_e32 v40, vcc, s2, v56
	s_mov_b64 s[2:3], 0xb000
	s_nop 0
	v_addc_co_u32_e32 v41, vcc, 0, v57, vcc
	v_add_co_u32_e32 v48, vcc, 0xb000, v56
	v_lshl_add_u64 v[52:53], v[56:57], 0, s[2:3]
	s_nop 0
	v_addc_co_u32_e32 v49, vcc, 0, v57, vcc
	s_mov_b64 s[2:3], 0xdc00
	global_load_dwordx4 v[8:11], v[8:9], off offset:3072
	s_nop 0
	global_load_dwordx4 v[12:15], v[12:13], off offset:16
	s_nop 0
	global_load_dwordx4 v[16:19], v[56:57], off offset:16
	global_load_dwordx4 v[20:23], v[56:57], off
	v_lshl_add_u64 v[60:61], v[56:57], 0, s[2:3]
	v_add_co_u32_e32 v56, vcc, 0xd000, v56
	global_load_dwordx4 v[24:27], v[24:25], off offset:3072
	s_nop 0
	global_load_dwordx4 v[28:31], v[28:29], off offset:16
	v_addc_co_u32_e32 v57, vcc, 0, v57, vcc
	global_load_dwordx4 v[32:35], v[32:33], off offset:2048
	s_nop 0
	global_load_dwordx4 v[36:39], v[36:37], off offset:16
	s_nop 0
	global_load_dwordx4 v[40:43], v[40:41], off offset:1024
	s_nop 0
	global_load_dwordx4 v[44:47], v[44:45], off offset:16
	s_nop 0
	global_load_dwordx4 v[48:51], v[48:49], off
	s_nop 0
	global_load_dwordx4 v[52:55], v[52:53], off offset:16
	s_nop 0
	global_load_dwordx4 v[56:59], v[56:57], off offset:3072
	s_nop 0
	global_load_dwordx4 v[60:63], v[60:61], off offset:16
	s_and_b32 s27, s87, 7
	s_lshl_b32 s27, s27, 5
	s_lshr_b32 s100, s87, 3
	s_or_b32 s27, s27, s100
	s_cmpk_gt_i32 s27, 0xff
	s_cbranch_scc1 .LBB0_1254
	v_lshlrev_b64 v[92:93], 1, v[64:65]
	v_lshl_add_u64 v[64:65], s[16:17], 0, v[92:93]
	s_mov_b64 s[2:3], 0x8400000
	v_lshl_add_u64 v[94:95], v[64:65], 0, s[2:3]
	s_mov_b64 s[2:3], 0x7e68000
	v_lshl_add_u64 v[96:97], v[64:65], 0, s[2:3]
	s_mov_b64 s[2:3], 0x13400000
	v_readlane_b32 s38, v255, 39
	v_lshl_add_u64 v[98:99], v[64:65], 0, s[2:3]
	s_lshl_b32 s29, s27, 6
	v_readlane_b32 s39, v255, 40
	s_branch .LBB0_1243
